# v92 + YG stores of the S2 epilogue written through (sc1) so the seam-3 L2 writeback finds less dirty data
# speedup vs baseline: 1.0137x; 1.0004x over previous
.LBB0_432:
	v_mul_f32_e32 v152, 0x3d372713, v126
	v_mul_f32_e32 v153, 0x3d372713, v127
	v_mul_f32_e32 v152, v126, v152
	v_mul_f32_e32 v153, v127, v153
	v_mul_f32_e32 v156, 0x3d372713, v122
	v_mul_f32_e32 v157, 0x3d372713, v123
	v_fma_f32 v152, v126, v152, v126
	v_fma_f32 v153, v127, v153, v127
	v_mul_f32_e32 v156, v122, v156
	v_mul_f32_e32 v157, v123, v157
	v_mul_f32_e32 v152, 0x3fcc422a, v152
	v_mul_f32_e32 v153, 0x3fcc422a, v153
	v_fma_f32 v156, v122, v156, v122
	v_fma_f32 v157, v123, v157, v123
	v_mul_f32_e32 v152, 0xbfb8aa3b, v152
	v_mul_f32_e32 v153, 0xbfb8aa3b, v153
	v_mul_f32_e32 v156, 0x3fcc422a, v156
	v_mul_f32_e32 v157, 0x3fcc422a, v157
	v_exp_f32_e32 v152, v152
	v_exp_f32_e32 v153, v153
	v_mul_f32_e32 v154, 0x3d372713, v128
	v_mul_f32_e32 v155, 0x3d372713, v129
	v_mul_f32_e32 v156, 0xbfb8aa3b, v156
	v_mul_f32_e32 v157, 0xbfb8aa3b, v157
	v_mul_f32_e32 v158, 0x3d372713, v124
	v_mul_f32_e32 v159, 0x3d372713, v125
	v_mul_f32_e32 v154, v128, v154
	v_mul_f32_e32 v155, v129, v155
	v_exp_f32_e32 v156, v156
	v_exp_f32_e32 v157, v157
	v_mul_f32_e32 v158, v124, v158
	v_mul_f32_e32 v159, v125, v159
	v_fma_f32 v154, v128, v154, v128
	v_fma_f32 v155, v129, v155, v129
	v_fma_f32 v158, v124, v158, v124
	v_fma_f32 v159, v125, v159, v125
	v_mul_f32_e32 v154, 0x3fcc422a, v154
	v_mul_f32_e32 v155, 0x3fcc422a, v155
	v_mul_f32_e32 v158, 0x3fcc422a, v158
	v_mul_f32_e32 v159, 0x3fcc422a, v159
	v_add_f32_e32 v152, 1.0, v152
	v_add_f32_e32 v153, 1.0, v153
	v_mul_f32_e32 v154, 0xbfb8aa3b, v154
	v_mul_f32_e32 v155, 0xbfb8aa3b, v155
	v_mul_f32_e32 v158, 0xbfb8aa3b, v158
	v_mul_f32_e32 v159, 0xbfb8aa3b, v159
	v_rcp_f32_e32 v152, v152
	v_exp_f32_e32 v154, v154
	v_exp_f32_e32 v155, v155
	v_rcp_f32_e32 v153, v153
	v_add_f32_e32 v156, 1.0, v156
	v_add_f32_e32 v157, 1.0, v157
	v_exp_f32_e32 v158, v158
	v_exp_f32_e32 v159, v159
	s_lshl_b32 s11, s82, 8
	v_rcp_f32_e32 v156, v156
	v_rcp_f32_e32 v157, v157
	s_lshl_b32 s10, s81, 8
	s_and_b32 s11, s11, 0x100
	s_and_b32 s10, s10, 0x100
	v_or_b32_e32 v150, s11, v144
	v_add_lshl_u32 v151, s10, v1, 5
	v_lshrrev_b32_e32 v150, 4, v150
	v_add_f32_e32 v154, 1.0, v154
	v_add_f32_e32 v155, 1.0, v155
	v_add_f32_e32 v158, 1.0, v158
	v_add_f32_e32 v159, 1.0, v159
	v_pk_mul_f32 v[126:127], v[126:127], v[152:153]
	s_lshl_b32 s10, s81, 3
	v_rcp_f32_e32 v154, v154
	v_rcp_f32_e32 v155, v155
	v_rcp_f32_e32 v158, v158
	v_rcp_f32_e32 v159, v159
	v_pk_mul_f32 v[152:153], v[122:123], v[156:157]
	v_cvt_pk_bf16_f32 v122, v126, v127
	v_or_b32_e32 v126, v151, v150
	s_and_b32 s20, s10, -16
	v_ashrrev_i32_e32 v127, 31, v126
	s_ashr_i32 s21, s20, 31
	v_lshlrev_b64 v[126:127], 10, v[126:127]
	v_lshl_add_u64 v[126:127], s[76:77], 0, v[126:127]
	s_lshl_b64 s[20:21], s[20:21], 1
	v_pk_mul_f32 v[128:129], v[128:129], v[154:155]
	v_pk_mul_f32 v[154:155], v[124:125], v[158:159]
	v_lshl_add_u64 v[126:127], v[126:127], 0, s[20:21]
	v_cvt_pk_bf16_f32 v123, v128, v129
	v_cvt_pk_bf16_f32 v124, v152, v153
	v_cvt_pk_bf16_f32 v125, v154, v155
	v_lshl_add_u64 v[126:127], v[126:127], 0, v[138:139]
	global_store_dwordx4 v[126:127], v[122:125], off sc1
	s_and_b64 vcc, exec, s[0:1]
	s_mov_b64 s[0:1], -1
	v_mul_f32_e32 v122, 0x3d372713, v118
	v_mul_f32_e32 v122, v118, v122
	v_fma_f32 v122, v118, v122, v118
	v_mul_f32_e32 v122, 0x3fcc422a, v122
	v_mul_f32_e32 v122, 0xbfb8aa3b, v122
	v_exp_f32_e32 v123, v122
	v_mul_f32_e32 v122, 0x3d372713, v119
	v_mul_f32_e32 v122, v119, v122
	v_fma_f32 v122, v119, v122, v119
	v_mul_f32_e32 v122, 0x3fcc422a, v122
	v_mul_f32_e32 v122, 0xbfb8aa3b, v122
	v_exp_f32_e32 v125, v122
	v_add_f32_e32 v123, 1.0, v123
	v_rcp_f32_e32 v124, v123
	v_or_b32_e32 v122, 8, v150
	v_add_f32_e32 v123, 1.0, v125
	v_mul_f32_e32 v125, 0x3d372713, v120
	v_mul_f32_e32 v125, v120, v125
	v_fma_f32 v125, v120, v125, v120
	v_mul_f32_e32 v125, 0x3fcc422a, v125
	v_mul_f32_e32 v125, 0xbfb8aa3b, v125
	v_exp_f32_e32 v126, v125
	v_mul_f32_e32 v125, 0x3d372713, v121
	v_mul_f32_e32 v125, v121, v125
	v_fma_f32 v125, v121, v125, v121
	v_mul_f32_e32 v125, 0x3fcc422a, v125
	v_mul_f32_e32 v125, 0xbfb8aa3b, v125
	v_exp_f32_e32 v127, v125
	v_rcp_f32_e32 v125, v123
	v_add_f32_e32 v123, 1.0, v126
	v_rcp_f32_e32 v126, v123
	v_add_f32_e32 v123, 1.0, v127
	v_mul_f32_e32 v127, 0x3d372713, v114
	v_mul_f32_e32 v127, v114, v127
	v_fma_f32 v127, v114, v127, v114
	v_mul_f32_e32 v127, 0x3fcc422a, v127
	v_mul_f32_e32 v127, 0xbfb8aa3b, v127
	v_exp_f32_e32 v128, v127
	v_mul_f32_e32 v127, 0x3d372713, v115
	v_mul_f32_e32 v127, v115, v127
	v_fma_f32 v127, v115, v127, v115
	v_mul_f32_e32 v127, 0x3fcc422a, v127
	v_mul_f32_e32 v127, 0xbfb8aa3b, v127
	v_exp_f32_e32 v129, v127
	v_rcp_f32_e32 v127, v123
	v_add_f32_e32 v123, 1.0, v128
	v_rcp_f32_e32 v128, v123
	v_add_f32_e32 v123, 1.0, v129
	v_mul_f32_e32 v129, 0x3d372713, v116
	v_mul_f32_e32 v129, v116, v129
	v_fma_f32 v129, v116, v129, v116
	v_mul_f32_e32 v129, 0x3fcc422a, v129
	v_mul_f32_e32 v129, 0xbfb8aa3b, v129
	v_exp_f32_e32 v152, v129
	v_mul_f32_e32 v129, 0x3d372713, v117
	v_mul_f32_e32 v129, v117, v129
	v_fma_f32 v129, v117, v129, v117
	v_mul_f32_e32 v129, 0x3fcc422a, v129
	v_mul_f32_e32 v129, 0xbfb8aa3b, v129
	v_exp_f32_e32 v153, v129
	v_rcp_f32_e32 v129, v123
	v_add_f32_e32 v123, 1.0, v152
	v_rcp_f32_e32 v152, v123
	v_add_f32_e32 v123, 1.0, v153
	v_pk_mul_f32 v[118:119], v[118:119], v[124:125]
	v_rcp_f32_e32 v153, v123
	v_pk_mul_f32 v[124:125], v[114:115], v[128:129]
	v_cvt_pk_bf16_f32 v114, v118, v119
	v_or_b32_e32 v118, v122, v151
	v_ashrrev_i32_e32 v119, 31, v118
	v_lshlrev_b64 v[118:119], 10, v[118:119]
	v_lshl_add_u64 v[118:119], s[76:77], 0, v[118:119]
	v_pk_mul_f32 v[120:121], v[120:121], v[126:127]
	v_pk_mul_f32 v[126:127], v[116:117], v[152:153]
	v_lshl_add_u64 v[118:119], v[118:119], 0, s[20:21]
	v_cvt_pk_bf16_f32 v115, v120, v121
	v_cvt_pk_bf16_f32 v116, v124, v125
	v_cvt_pk_bf16_f32 v117, v126, v127
	v_lshl_add_u64 v[118:119], v[118:119], 0, v[138:139]
	global_store_dwordx4 v[118:119], v[114:117], off sc1
	v_mul_f32_e32 v118, 0x3d372713, v106
	v_mul_f32_e32 v119, 0x3d372713, v107
	v_mul_f32_e32 v114, 0x3d372713, v110
	v_mul_f32_e32 v115, 0x3d372713, v111
	v_mul_f32_e32 v114, v110, v114
	v_mul_f32_e32 v115, v111, v115
	v_mul_f32_e32 v116, 0x3d372713, v112
	v_mul_f32_e32 v117, 0x3d372713, v113
	v_fma_f32 v114, v110, v114, v110
	v_fma_f32 v115, v111, v115, v111
	v_mul_f32_e32 v116, v112, v116
	v_mul_f32_e32 v117, v113, v117
	v_mul_f32_e32 v118, v106, v118
	v_mul_f32_e32 v119, v107, v119
	v_mul_f32_e32 v114, 0x3fcc422a, v114
	v_mul_f32_e32 v115, 0x3fcc422a, v115
	v_fma_f32 v116, v112, v116, v112
	v_fma_f32 v117, v113, v117, v113
	v_fma_f32 v118, v106, v118, v106
	v_fma_f32 v119, v107, v119, v107
	v_mul_f32_e32 v114, 0xbfb8aa3b, v114
	v_mul_f32_e32 v115, 0xbfb8aa3b, v115
	v_mul_f32_e32 v116, 0x3fcc422a, v116
	v_mul_f32_e32 v117, 0x3fcc422a, v117
	v_mul_f32_e32 v118, 0x3fcc422a, v118
	v_mul_f32_e32 v119, 0x3fcc422a, v119
	v_exp_f32_e32 v114, v114
	v_exp_f32_e32 v115, v115
	v_mul_f32_e32 v116, 0xbfb8aa3b, v116
	v_mul_f32_e32 v117, 0xbfb8aa3b, v117
	v_mul_f32_e32 v118, 0xbfb8aa3b, v118
	v_mul_f32_e32 v119, 0xbfb8aa3b, v119
	v_mul_f32_e32 v120, 0x3d372713, v108
	v_mul_f32_e32 v121, 0x3d372713, v109
	v_exp_f32_e32 v116, v116
	v_exp_f32_e32 v117, v117
	v_exp_f32_e32 v118, v118
	v_exp_f32_e32 v119, v119
	v_mul_f32_e32 v120, v108, v120
	v_mul_f32_e32 v121, v109, v121
	v_fma_f32 v120, v108, v120, v108
	v_fma_f32 v121, v109, v121, v109
	v_mul_f32_e32 v120, 0x3fcc422a, v120
	v_mul_f32_e32 v121, 0x3fcc422a, v121
	v_add_f32_e32 v114, 1.0, v114
	v_add_f32_e32 v115, 1.0, v115
	v_mul_f32_e32 v120, 0xbfb8aa3b, v120
	v_mul_f32_e32 v121, 0xbfb8aa3b, v121
	v_rcp_f32_e32 v114, v114
	v_rcp_f32_e32 v115, v115
	v_add_f32_e32 v116, 1.0, v116
	v_add_f32_e32 v117, 1.0, v117
	v_add_f32_e32 v118, 1.0, v118
	v_add_f32_e32 v119, 1.0, v119
	v_exp_f32_e32 v120, v120
	v_exp_f32_e32 v121, v121
	v_rcp_f32_e32 v116, v116
	v_rcp_f32_e32 v117, v117
	v_rcp_f32_e32 v118, v118
	v_rcp_f32_e32 v119, v119
	v_or_b32_e32 v123, 0x200, v151
	v_add_f32_e32 v120, 1.0, v120
	v_add_f32_e32 v121, 1.0, v121
	v_pk_mul_f32 v[110:111], v[110:111], v[114:115]
	v_rcp_f32_e32 v120, v120
	v_rcp_f32_e32 v121, v121
	v_pk_mul_f32 v[112:113], v[112:113], v[116:117]
	v_pk_mul_f32 v[114:115], v[106:107], v[118:119]
	v_cvt_pk_bf16_f32 v106, v110, v111
	v_or_b32_e32 v110, v123, v150
	v_cvt_pk_bf16_f32 v107, v112, v113
	v_ashrrev_i32_e32 v111, 31, v110
	v_mul_f32_e32 v112, 0x3d372713, v102
	v_mul_f32_e32 v113, 0x3d372713, v103
	v_lshlrev_b64 v[110:111], 10, v[110:111]
	v_mul_f32_e32 v112, v102, v112
	v_mul_f32_e32 v113, v103, v113
	v_lshl_add_u64 v[110:111], s[76:77], 0, v[110:111]
	v_fma_f32 v112, v102, v112, v102
	v_fma_f32 v113, v103, v113, v103
	v_pk_mul_f32 v[116:117], v[108:109], v[120:121]
	v_lshl_add_u64 v[110:111], v[110:111], 0, s[20:21]
	v_mul_f32_e32 v112, 0x3fcc422a, v112
	v_mul_f32_e32 v113, 0x3fcc422a, v113
	v_cvt_pk_bf16_f32 v108, v114, v115
	v_cvt_pk_bf16_f32 v109, v116, v117
	v_lshl_add_u64 v[110:111], v[110:111], 0, v[138:139]
	v_mul_f32_e32 v112, 0xbfb8aa3b, v112
	v_mul_f32_e32 v113, 0xbfb8aa3b, v113
	v_exp_f32_e32 v112, v112
	v_exp_f32_e32 v113, v113
	global_store_dwordx4 v[110:111], v[106:109], off sc1
	v_mul_f32_e32 v110, 0x3d372713, v98
	v_mul_f32_e32 v111, 0x3d372713, v99
	v_mul_f32_e32 v110, v98, v110
	v_mul_f32_e32 v111, v99, v111
	v_fma_f32 v110, v98, v110, v98
	v_fma_f32 v111, v99, v111, v99
	v_mul_f32_e32 v110, 0x3fcc422a, v110
	v_mul_f32_e32 v111, 0x3fcc422a, v111
	v_add_f32_e32 v106, 1.0, v112
	v_add_f32_e32 v107, 1.0, v113
	v_mul_f32_e32 v108, 0x3d372713, v104
	v_mul_f32_e32 v109, 0x3d372713, v105
	v_mul_f32_e32 v110, 0xbfb8aa3b, v110
	v_mul_f32_e32 v111, 0xbfb8aa3b, v111
	v_mul_f32_e32 v112, 0x3d372713, v100
	v_mul_f32_e32 v113, 0x3d372713, v101
	v_mul_f32_e32 v108, v104, v108
	v_mul_f32_e32 v109, v105, v109
	v_exp_f32_e32 v110, v110
	v_exp_f32_e32 v111, v111
	v_mul_f32_e32 v112, v100, v112
	v_mul_f32_e32 v113, v101, v113
	v_fma_f32 v108, v104, v108, v104
	v_fma_f32 v109, v105, v109, v105
	v_fma_f32 v112, v100, v112, v100
	v_fma_f32 v113, v101, v113, v101
	v_mul_f32_e32 v108, 0x3fcc422a, v108
	v_mul_f32_e32 v109, 0x3fcc422a, v109
	v_mul_f32_e32 v112, 0x3fcc422a, v112
	v_mul_f32_e32 v113, 0x3fcc422a, v113
	v_mul_f32_e32 v108, 0xbfb8aa3b, v108
	v_mul_f32_e32 v109, 0xbfb8aa3b, v109
	v_mul_f32_e32 v112, 0xbfb8aa3b, v112
	v_mul_f32_e32 v113, 0xbfb8aa3b, v113
	v_rcp_f32_e32 v106, v106
	v_exp_f32_e32 v108, v108
	v_exp_f32_e32 v109, v109
	v_rcp_f32_e32 v107, v107
	v_add_f32_e32 v110, 1.0, v110
	v_add_f32_e32 v111, 1.0, v111
	v_exp_f32_e32 v112, v112
	v_exp_f32_e32 v113, v113
	v_rcp_f32_e32 v110, v110
	v_rcp_f32_e32 v111, v111
	v_add_f32_e32 v108, 1.0, v108
	v_add_f32_e32 v109, 1.0, v109
	v_add_f32_e32 v112, 1.0, v112
	v_add_f32_e32 v113, 1.0, v113
	v_pk_mul_f32 v[102:103], v[102:103], v[106:107]
	v_rcp_f32_e32 v108, v108
	v_rcp_f32_e32 v109, v109
	v_rcp_f32_e32 v112, v112
	v_rcp_f32_e32 v113, v113
	v_pk_mul_f32 v[106:107], v[98:99], v[110:111]
	v_cvt_pk_bf16_f32 v98, v102, v103
	v_or_b32_e32 v102, v123, v122
	v_ashrrev_i32_e32 v103, 31, v102
	v_lshlrev_b64 v[102:103], 10, v[102:103]
	v_lshl_add_u64 v[102:103], s[76:77], 0, v[102:103]
	v_pk_mul_f32 v[104:105], v[104:105], v[108:109]
	v_pk_mul_f32 v[108:109], v[100:101], v[112:113]
	v_lshl_add_u64 v[102:103], v[102:103], 0, s[20:21]
	v_cvt_pk_bf16_f32 v99, v104, v105
	v_cvt_pk_bf16_f32 v100, v106, v107
	v_cvt_pk_bf16_f32 v101, v108, v109
	v_lshl_add_u64 v[102:103], v[102:103], 0, v[138:139]
	global_store_dwordx4 v[102:103], v[98:101], off sc1
	v_mul_f32_e32 v102, 0x3d372713, v90
	v_mul_f32_e32 v103, 0x3d372713, v91
	v_mul_f32_e32 v98, 0x3d372713, v94
	v_mul_f32_e32 v99, 0x3d372713, v95
	v_mul_f32_e32 v98, v94, v98
	v_mul_f32_e32 v99, v95, v99
	v_mul_f32_e32 v100, 0x3d372713, v96
	v_mul_f32_e32 v101, 0x3d372713, v97
	v_fma_f32 v98, v94, v98, v94
	v_fma_f32 v99, v95, v99, v95
	v_mul_f32_e32 v100, v96, v100
	v_mul_f32_e32 v101, v97, v101
	v_mul_f32_e32 v102, v90, v102
	v_mul_f32_e32 v103, v91, v103
	v_mul_f32_e32 v98, 0x3fcc422a, v98
	v_mul_f32_e32 v99, 0x3fcc422a, v99
	v_fma_f32 v100, v96, v100, v96
	v_fma_f32 v101, v97, v101, v97
	v_fma_f32 v102, v90, v102, v90
	v_fma_f32 v103, v91, v103, v91
	v_mul_f32_e32 v98, 0xbfb8aa3b, v98
	v_mul_f32_e32 v99, 0xbfb8aa3b, v99
	v_mul_f32_e32 v100, 0x3fcc422a, v100
	v_mul_f32_e32 v101, 0x3fcc422a, v101
	v_mul_f32_e32 v102, 0x3fcc422a, v102
	v_mul_f32_e32 v103, 0x3fcc422a, v103
	v_exp_f32_e32 v98, v98
	v_exp_f32_e32 v99, v99
	v_mul_f32_e32 v100, 0xbfb8aa3b, v100
	v_mul_f32_e32 v101, 0xbfb8aa3b, v101
	v_mul_f32_e32 v102, 0xbfb8aa3b, v102
	v_mul_f32_e32 v103, 0xbfb8aa3b, v103
	v_mul_f32_e32 v104, 0x3d372713, v92
	v_mul_f32_e32 v105, 0x3d372713, v93
	v_exp_f32_e32 v100, v100
	v_exp_f32_e32 v101, v101
	v_exp_f32_e32 v102, v102
	v_exp_f32_e32 v103, v103
	v_mul_f32_e32 v104, v92, v104
	v_mul_f32_e32 v105, v93, v105
	v_fma_f32 v104, v92, v104, v92
	v_fma_f32 v105, v93, v105, v93
	v_mul_f32_e32 v104, 0x3fcc422a, v104
	v_mul_f32_e32 v105, 0x3fcc422a, v105
	v_add_f32_e32 v98, 1.0, v98
	v_add_f32_e32 v99, 1.0, v99
	v_mul_f32_e32 v104, 0xbfb8aa3b, v104
	v_mul_f32_e32 v105, 0xbfb8aa3b, v105
	v_rcp_f32_e32 v98, v98
	v_rcp_f32_e32 v99, v99
	v_add_f32_e32 v100, 1.0, v100
	v_add_f32_e32 v101, 1.0, v101
	v_add_f32_e32 v102, 1.0, v102
	v_add_f32_e32 v103, 1.0, v103
	v_exp_f32_e32 v104, v104
	v_exp_f32_e32 v105, v105
	v_rcp_f32_e32 v100, v100
	v_rcp_f32_e32 v101, v101
	v_rcp_f32_e32 v102, v102
	v_rcp_f32_e32 v103, v103
	v_or_b32_e32 v106, 0x400, v151
	v_add_f32_e32 v104, 1.0, v104
	v_add_f32_e32 v105, 1.0, v105
	v_pk_mul_f32 v[94:95], v[94:95], v[98:99]
	v_rcp_f32_e32 v104, v104
	v_rcp_f32_e32 v105, v105
	v_pk_mul_f32 v[96:97], v[96:97], v[100:101]
	v_pk_mul_f32 v[98:99], v[90:91], v[102:103]
	v_cvt_pk_bf16_f32 v90, v94, v95
	v_or_b32_e32 v94, v106, v150
	v_cvt_pk_bf16_f32 v91, v96, v97
	v_ashrrev_i32_e32 v95, 31, v94
	v_mul_f32_e32 v96, 0x3d372713, v86
	v_mul_f32_e32 v97, 0x3d372713, v87
	v_lshlrev_b64 v[94:95], 10, v[94:95]
	v_mul_f32_e32 v96, v86, v96
	v_mul_f32_e32 v97, v87, v97
	v_lshl_add_u64 v[94:95], s[76:77], 0, v[94:95]
	v_fma_f32 v96, v86, v96, v86
	v_fma_f32 v97, v87, v97, v87
	v_pk_mul_f32 v[100:101], v[92:93], v[104:105]
	v_lshl_add_u64 v[94:95], v[94:95], 0, s[20:21]
	v_mul_f32_e32 v96, 0x3fcc422a, v96
	v_mul_f32_e32 v97, 0x3fcc422a, v97
	v_cvt_pk_bf16_f32 v92, v98, v99
	v_cvt_pk_bf16_f32 v93, v100, v101
	v_lshl_add_u64 v[94:95], v[94:95], 0, v[138:139]
	v_mul_f32_e32 v96, 0xbfb8aa3b, v96
	v_mul_f32_e32 v97, 0xbfb8aa3b, v97
	v_exp_f32_e32 v96, v96
	v_exp_f32_e32 v97, v97
	global_store_dwordx4 v[94:95], v[90:93], off sc1
	v_mul_f32_e32 v94, 0x3d372713, v82
	v_mul_f32_e32 v95, 0x3d372713, v83
	v_mul_f32_e32 v94, v82, v94
	v_mul_f32_e32 v95, v83, v95
	v_fma_f32 v94, v82, v94, v82
	v_fma_f32 v95, v83, v95, v83
	v_mul_f32_e32 v94, 0x3fcc422a, v94
	v_mul_f32_e32 v95, 0x3fcc422a, v95
	v_add_f32_e32 v90, 1.0, v96
	v_add_f32_e32 v91, 1.0, v97
	v_mul_f32_e32 v92, 0x3d372713, v88
	v_mul_f32_e32 v93, 0x3d372713, v89
	v_mul_f32_e32 v94, 0xbfb8aa3b, v94
	v_mul_f32_e32 v95, 0xbfb8aa3b, v95
	v_mul_f32_e32 v96, 0x3d372713, v84
	v_mul_f32_e32 v97, 0x3d372713, v85
	v_mul_f32_e32 v92, v88, v92
	v_mul_f32_e32 v93, v89, v93
	v_exp_f32_e32 v94, v94
	v_exp_f32_e32 v95, v95
	v_mul_f32_e32 v96, v84, v96
	v_mul_f32_e32 v97, v85, v97
	v_fma_f32 v92, v88, v92, v88
	v_fma_f32 v93, v89, v93, v89
	v_fma_f32 v96, v84, v96, v84
	v_fma_f32 v97, v85, v97, v85
	v_mul_f32_e32 v92, 0x3fcc422a, v92
	v_mul_f32_e32 v93, 0x3fcc422a, v93
	v_mul_f32_e32 v96, 0x3fcc422a, v96
	v_mul_f32_e32 v97, 0x3fcc422a, v97
	v_mul_f32_e32 v92, 0xbfb8aa3b, v92
	v_mul_f32_e32 v93, 0xbfb8aa3b, v93
	v_mul_f32_e32 v96, 0xbfb8aa3b, v96
	v_mul_f32_e32 v97, 0xbfb8aa3b, v97
	v_rcp_f32_e32 v90, v90
	v_exp_f32_e32 v92, v92
	v_exp_f32_e32 v93, v93
	v_rcp_f32_e32 v91, v91
	v_add_f32_e32 v94, 1.0, v94
	v_add_f32_e32 v95, 1.0, v95
	v_exp_f32_e32 v96, v96
	v_exp_f32_e32 v97, v97
	v_rcp_f32_e32 v94, v94
	v_rcp_f32_e32 v95, v95
	v_add_f32_e32 v92, 1.0, v92
	v_add_f32_e32 v93, 1.0, v93
	v_add_f32_e32 v96, 1.0, v96
	v_add_f32_e32 v97, 1.0, v97
	v_pk_mul_f32 v[86:87], v[86:87], v[90:91]
	v_rcp_f32_e32 v92, v92
	v_rcp_f32_e32 v93, v93
	v_rcp_f32_e32 v96, v96
	v_rcp_f32_e32 v97, v97
	v_pk_mul_f32 v[90:91], v[82:83], v[94:95]
	v_cvt_pk_bf16_f32 v82, v86, v87
	v_or_b32_e32 v86, v106, v122
	v_ashrrev_i32_e32 v87, 31, v86
	v_lshlrev_b64 v[86:87], 10, v[86:87]
	v_lshl_add_u64 v[86:87], s[76:77], 0, v[86:87]
	v_pk_mul_f32 v[88:89], v[88:89], v[92:93]
	v_pk_mul_f32 v[92:93], v[84:85], v[96:97]
	v_lshl_add_u64 v[86:87], v[86:87], 0, s[20:21]
	v_cvt_pk_bf16_f32 v83, v88, v89
	v_cvt_pk_bf16_f32 v84, v90, v91
	v_cvt_pk_bf16_f32 v85, v92, v93
	v_lshl_add_u64 v[86:87], v[86:87], 0, v[138:139]
	global_store_dwordx4 v[86:87], v[82:85], off sc1
	v_mul_f32_e32 v86, 0x3d372713, v74
	v_mul_f32_e32 v87, 0x3d372713, v75
	v_mul_f32_e32 v82, 0x3d372713, v78
	v_mul_f32_e32 v83, 0x3d372713, v79
	v_mul_f32_e32 v82, v78, v82
	v_mul_f32_e32 v83, v79, v83
	v_mul_f32_e32 v84, 0x3d372713, v80
	v_mul_f32_e32 v85, 0x3d372713, v81
	v_fma_f32 v82, v78, v82, v78
	v_fma_f32 v83, v79, v83, v79
	v_mul_f32_e32 v84, v80, v84
	v_mul_f32_e32 v85, v81, v85
	v_mul_f32_e32 v86, v74, v86
	v_mul_f32_e32 v87, v75, v87
	v_mul_f32_e32 v82, 0x3fcc422a, v82
	v_mul_f32_e32 v83, 0x3fcc422a, v83
	v_fma_f32 v84, v80, v84, v80
	v_fma_f32 v85, v81, v85, v81
	v_fma_f32 v86, v74, v86, v74
	v_fma_f32 v87, v75, v87, v75
	v_mul_f32_e32 v82, 0xbfb8aa3b, v82
	v_mul_f32_e32 v83, 0xbfb8aa3b, v83
	v_mul_f32_e32 v84, 0x3fcc422a, v84
	v_mul_f32_e32 v85, 0x3fcc422a, v85
	v_mul_f32_e32 v86, 0x3fcc422a, v86
	v_mul_f32_e32 v87, 0x3fcc422a, v87
	v_exp_f32_e32 v82, v82
	v_exp_f32_e32 v83, v83
	v_mul_f32_e32 v84, 0xbfb8aa3b, v84
	v_mul_f32_e32 v85, 0xbfb8aa3b, v85
	v_mul_f32_e32 v86, 0xbfb8aa3b, v86
	v_mul_f32_e32 v87, 0xbfb8aa3b, v87
	v_mul_f32_e32 v88, 0x3d372713, v76
	v_mul_f32_e32 v89, 0x3d372713, v77
	v_exp_f32_e32 v84, v84
	v_exp_f32_e32 v85, v85
	v_exp_f32_e32 v86, v86
	v_exp_f32_e32 v87, v87
	v_mul_f32_e32 v88, v76, v88
	v_mul_f32_e32 v89, v77, v89
	v_fma_f32 v88, v76, v88, v76
	v_fma_f32 v89, v77, v89, v77
	v_mul_f32_e32 v88, 0x3fcc422a, v88
	v_mul_f32_e32 v89, 0x3fcc422a, v89
	v_add_f32_e32 v82, 1.0, v82
	v_add_f32_e32 v83, 1.0, v83
	v_mul_f32_e32 v88, 0xbfb8aa3b, v88
	v_mul_f32_e32 v89, 0xbfb8aa3b, v89
	v_rcp_f32_e32 v82, v82
	v_rcp_f32_e32 v83, v83
	v_add_f32_e32 v84, 1.0, v84
	v_add_f32_e32 v85, 1.0, v85
	v_add_f32_e32 v86, 1.0, v86
	v_add_f32_e32 v87, 1.0, v87
	v_exp_f32_e32 v88, v88
	v_exp_f32_e32 v89, v89
	v_rcp_f32_e32 v84, v84
	v_rcp_f32_e32 v85, v85
	v_rcp_f32_e32 v86, v86
	v_rcp_f32_e32 v87, v87
	v_or_b32_e32 v90, 0x600, v151
	v_add_f32_e32 v88, 1.0, v88
	v_add_f32_e32 v89, 1.0, v89
	v_pk_mul_f32 v[78:79], v[78:79], v[82:83]
	v_rcp_f32_e32 v88, v88
	v_rcp_f32_e32 v89, v89
	v_pk_mul_f32 v[80:81], v[80:81], v[84:85]
	v_pk_mul_f32 v[82:83], v[74:75], v[86:87]
	v_cvt_pk_bf16_f32 v74, v78, v79
	v_or_b32_e32 v78, v90, v150
	v_cvt_pk_bf16_f32 v75, v80, v81
	v_ashrrev_i32_e32 v79, 31, v78
	v_mul_f32_e32 v80, 0x3d372713, v70
	v_mul_f32_e32 v81, 0x3d372713, v71
	v_lshlrev_b64 v[78:79], 10, v[78:79]
	v_mul_f32_e32 v80, v70, v80
	v_mul_f32_e32 v81, v71, v81
	v_lshl_add_u64 v[78:79], s[76:77], 0, v[78:79]
	v_fma_f32 v80, v70, v80, v70
	v_fma_f32 v81, v71, v81, v71
	v_pk_mul_f32 v[84:85], v[76:77], v[88:89]
	v_lshl_add_u64 v[78:79], v[78:79], 0, s[20:21]
	v_mul_f32_e32 v80, 0x3fcc422a, v80
	v_mul_f32_e32 v81, 0x3fcc422a, v81
	v_cvt_pk_bf16_f32 v76, v82, v83
	v_cvt_pk_bf16_f32 v77, v84, v85
	v_lshl_add_u64 v[78:79], v[78:79], 0, v[138:139]
	v_mul_f32_e32 v80, 0xbfb8aa3b, v80
	v_mul_f32_e32 v81, 0xbfb8aa3b, v81
	v_exp_f32_e32 v80, v80
	v_exp_f32_e32 v81, v81
	global_store_dwordx4 v[78:79], v[74:77], off sc1
	v_mul_f32_e32 v78, 0x3d372713, v66
	v_mul_f32_e32 v79, 0x3d372713, v67
	v_mul_f32_e32 v78, v66, v78
	v_mul_f32_e32 v79, v67, v79
	v_fma_f32 v78, v66, v78, v66
	v_fma_f32 v79, v67, v79, v67
	v_mul_f32_e32 v78, 0x3fcc422a, v78
	v_mul_f32_e32 v79, 0x3fcc422a, v79
	v_add_f32_e32 v74, 1.0, v80
	v_add_f32_e32 v75, 1.0, v81
	v_mul_f32_e32 v76, 0x3d372713, v72
	v_mul_f32_e32 v77, 0x3d372713, v73
	v_mul_f32_e32 v78, 0xbfb8aa3b, v78
	v_mul_f32_e32 v79, 0xbfb8aa3b, v79
	v_mul_f32_e32 v80, 0x3d372713, v68
	v_mul_f32_e32 v81, 0x3d372713, v69
	v_mul_f32_e32 v76, v72, v76
	v_mul_f32_e32 v77, v73, v77
	v_exp_f32_e32 v78, v78
	v_exp_f32_e32 v79, v79
	v_mul_f32_e32 v80, v68, v80
	v_mul_f32_e32 v81, v69, v81
	v_fma_f32 v76, v72, v76, v72
	v_fma_f32 v77, v73, v77, v73
	v_fma_f32 v80, v68, v80, v68
	v_fma_f32 v81, v69, v81, v69
	v_mul_f32_e32 v76, 0x3fcc422a, v76
	v_mul_f32_e32 v77, 0x3fcc422a, v77
	v_mul_f32_e32 v80, 0x3fcc422a, v80
	v_mul_f32_e32 v81, 0x3fcc422a, v81
	v_mul_f32_e32 v76, 0xbfb8aa3b, v76
	v_mul_f32_e32 v77, 0xbfb8aa3b, v77
	v_mul_f32_e32 v80, 0xbfb8aa3b, v80
	v_mul_f32_e32 v81, 0xbfb8aa3b, v81
	v_rcp_f32_e32 v74, v74
	v_exp_f32_e32 v76, v76
	v_exp_f32_e32 v77, v77
	v_rcp_f32_e32 v75, v75
	v_add_f32_e32 v78, 1.0, v78
	v_add_f32_e32 v79, 1.0, v79
	v_exp_f32_e32 v80, v80
	v_exp_f32_e32 v81, v81
	v_rcp_f32_e32 v78, v78
	v_rcp_f32_e32 v79, v79
	v_add_f32_e32 v76, 1.0, v76
	v_add_f32_e32 v77, 1.0, v77
	v_add_f32_e32 v80, 1.0, v80
	v_add_f32_e32 v81, 1.0, v81
	v_pk_mul_f32 v[70:71], v[70:71], v[74:75]
	v_rcp_f32_e32 v76, v76
	v_rcp_f32_e32 v77, v77
	v_rcp_f32_e32 v80, v80
	v_rcp_f32_e32 v81, v81
	v_pk_mul_f32 v[74:75], v[66:67], v[78:79]
	v_cvt_pk_bf16_f32 v66, v70, v71
	v_or_b32_e32 v70, v90, v122
	v_ashrrev_i32_e32 v71, 31, v70
	v_lshlrev_b64 v[70:71], 10, v[70:71]
	v_lshl_add_u64 v[70:71], s[76:77], 0, v[70:71]
	v_pk_mul_f32 v[72:73], v[72:73], v[76:77]
	v_pk_mul_f32 v[76:77], v[68:69], v[80:81]
	v_lshl_add_u64 v[70:71], v[70:71], 0, s[20:21]
	v_cvt_pk_bf16_f32 v67, v72, v73
	v_cvt_pk_bf16_f32 v68, v74, v75
	v_cvt_pk_bf16_f32 v69, v76, v77
	v_lshl_add_u64 v[70:71], v[70:71], 0, v[138:139]
	global_store_dwordx4 v[70:71], v[66:69], off sc1
	v_mul_f32_e32 v70, 0x3d372713, v58
	v_mul_f32_e32 v71, 0x3d372713, v59
	v_mul_f32_e32 v66, 0x3d372713, v62
	v_mul_f32_e32 v67, 0x3d372713, v63
	v_mul_f32_e32 v66, v62, v66
	v_mul_f32_e32 v67, v63, v67
	v_mul_f32_e32 v68, 0x3d372713, v64
	v_mul_f32_e32 v69, 0x3d372713, v65
	v_fma_f32 v66, v62, v66, v62
	v_fma_f32 v67, v63, v67, v63
	v_mul_f32_e32 v68, v64, v68
	v_mul_f32_e32 v69, v65, v69
	v_mul_f32_e32 v70, v58, v70
	v_mul_f32_e32 v71, v59, v71
	v_mul_f32_e32 v66, 0x3fcc422a, v66
	v_mul_f32_e32 v67, 0x3fcc422a, v67
	v_fma_f32 v68, v64, v68, v64
	v_fma_f32 v69, v65, v69, v65
	v_fma_f32 v70, v58, v70, v58
	v_fma_f32 v71, v59, v71, v59
	v_mul_f32_e32 v66, 0xbfb8aa3b, v66
	v_mul_f32_e32 v67, 0xbfb8aa3b, v67
	v_mul_f32_e32 v68, 0x3fcc422a, v68
	v_mul_f32_e32 v69, 0x3fcc422a, v69
	v_mul_f32_e32 v70, 0x3fcc422a, v70
	v_mul_f32_e32 v71, 0x3fcc422a, v71
	v_exp_f32_e32 v66, v66
	v_exp_f32_e32 v67, v67
	v_mul_f32_e32 v68, 0xbfb8aa3b, v68
	v_mul_f32_e32 v69, 0xbfb8aa3b, v69
	v_mul_f32_e32 v70, 0xbfb8aa3b, v70
	v_mul_f32_e32 v71, 0xbfb8aa3b, v71
	v_mul_f32_e32 v72, 0x3d372713, v60
	v_mul_f32_e32 v73, 0x3d372713, v61
	v_exp_f32_e32 v68, v68
	v_exp_f32_e32 v69, v69
	v_exp_f32_e32 v70, v70
	v_exp_f32_e32 v71, v71
	v_mul_f32_e32 v72, v60, v72
	v_mul_f32_e32 v73, v61, v73
	v_fma_f32 v72, v60, v72, v60
	v_fma_f32 v73, v61, v73, v61
	v_mul_f32_e32 v72, 0x3fcc422a, v72
	v_mul_f32_e32 v73, 0x3fcc422a, v73
	v_add_f32_e32 v66, 1.0, v66
	v_add_f32_e32 v67, 1.0, v67
	v_mul_f32_e32 v72, 0xbfb8aa3b, v72
	v_mul_f32_e32 v73, 0xbfb8aa3b, v73
	v_rcp_f32_e32 v66, v66
	v_rcp_f32_e32 v67, v67
	v_add_f32_e32 v68, 1.0, v68
	v_add_f32_e32 v69, 1.0, v69
	v_add_f32_e32 v70, 1.0, v70
	v_add_f32_e32 v71, 1.0, v71
	v_exp_f32_e32 v72, v72
	v_exp_f32_e32 v73, v73
	v_rcp_f32_e32 v68, v68
	v_rcp_f32_e32 v69, v69
	v_rcp_f32_e32 v70, v70
	v_rcp_f32_e32 v71, v71
	v_add_u32_e32 v74, 0x1000, v151
	v_add_f32_e32 v72, 1.0, v72
	v_add_f32_e32 v73, 1.0, v73
	v_pk_mul_f32 v[62:63], v[62:63], v[66:67]
	v_rcp_f32_e32 v72, v72
	v_rcp_f32_e32 v73, v73
	v_pk_mul_f32 v[64:65], v[64:65], v[68:69]
	v_pk_mul_f32 v[66:67], v[58:59], v[70:71]
	v_cvt_pk_bf16_f32 v58, v62, v63
	v_or_b32_e32 v62, v74, v150
	v_cvt_pk_bf16_f32 v59, v64, v65
	v_ashrrev_i32_e32 v63, 31, v62
	v_mul_f32_e32 v64, 0x3d372713, v54
	v_mul_f32_e32 v65, 0x3d372713, v55
	v_lshlrev_b64 v[62:63], 10, v[62:63]
	v_mul_f32_e32 v64, v54, v64
	v_mul_f32_e32 v65, v55, v65
	v_lshl_add_u64 v[62:63], s[76:77], 0, v[62:63]
	v_fma_f32 v64, v54, v64, v54
	v_fma_f32 v65, v55, v65, v55
	v_pk_mul_f32 v[68:69], v[60:61], v[72:73]
	v_lshl_add_u64 v[62:63], v[62:63], 0, s[20:21]
	v_mul_f32_e32 v64, 0x3fcc422a, v64
	v_mul_f32_e32 v65, 0x3fcc422a, v65
	v_cvt_pk_bf16_f32 v60, v66, v67
	v_cvt_pk_bf16_f32 v61, v68, v69
	v_lshl_add_u64 v[62:63], v[62:63], 0, v[138:139]
	v_mul_f32_e32 v64, 0xbfb8aa3b, v64
	v_mul_f32_e32 v65, 0xbfb8aa3b, v65
	v_exp_f32_e32 v64, v64
	v_exp_f32_e32 v65, v65
	global_store_dwordx4 v[62:63], v[58:61], off sc1
	v_mul_f32_e32 v62, 0x3d372713, v50
	v_mul_f32_e32 v63, 0x3d372713, v51
	v_mul_f32_e32 v62, v50, v62
	v_mul_f32_e32 v63, v51, v63
	v_fma_f32 v62, v50, v62, v50
	v_fma_f32 v63, v51, v63, v51
	v_mul_f32_e32 v62, 0x3fcc422a, v62
	v_mul_f32_e32 v63, 0x3fcc422a, v63
	v_add_f32_e32 v58, 1.0, v64
	v_add_f32_e32 v59, 1.0, v65
	v_mul_f32_e32 v60, 0x3d372713, v56
	v_mul_f32_e32 v61, 0x3d372713, v57
	v_mul_f32_e32 v62, 0xbfb8aa3b, v62
	v_mul_f32_e32 v63, 0xbfb8aa3b, v63
	v_mul_f32_e32 v64, 0x3d372713, v52
	v_mul_f32_e32 v65, 0x3d372713, v53
	v_mul_f32_e32 v60, v56, v60
	v_mul_f32_e32 v61, v57, v61
	v_exp_f32_e32 v62, v62
	v_exp_f32_e32 v63, v63
	v_mul_f32_e32 v64, v52, v64
	v_mul_f32_e32 v65, v53, v65
	v_fma_f32 v60, v56, v60, v56
	v_fma_f32 v61, v57, v61, v57
	v_fma_f32 v64, v52, v64, v52
	v_fma_f32 v65, v53, v65, v53
	v_mul_f32_e32 v60, 0x3fcc422a, v60
	v_mul_f32_e32 v61, 0x3fcc422a, v61
	v_mul_f32_e32 v64, 0x3fcc422a, v64
	v_mul_f32_e32 v65, 0x3fcc422a, v65
	v_mul_f32_e32 v60, 0xbfb8aa3b, v60
	v_mul_f32_e32 v61, 0xbfb8aa3b, v61
	v_mul_f32_e32 v64, 0xbfb8aa3b, v64
	v_mul_f32_e32 v65, 0xbfb8aa3b, v65
	v_rcp_f32_e32 v58, v58
	v_exp_f32_e32 v60, v60
	v_exp_f32_e32 v61, v61
	v_rcp_f32_e32 v59, v59
	v_add_f32_e32 v62, 1.0, v62
	v_add_f32_e32 v63, 1.0, v63
	v_exp_f32_e32 v64, v64
	v_exp_f32_e32 v65, v65
	v_rcp_f32_e32 v62, v62
	v_rcp_f32_e32 v63, v63
	v_add_f32_e32 v60, 1.0, v60
	v_add_f32_e32 v61, 1.0, v61
	v_add_f32_e32 v64, 1.0, v64
	v_add_f32_e32 v65, 1.0, v65
	v_pk_mul_f32 v[54:55], v[54:55], v[58:59]
	v_rcp_f32_e32 v60, v60
	v_rcp_f32_e32 v61, v61
	v_rcp_f32_e32 v64, v64
	v_rcp_f32_e32 v65, v65
	v_pk_mul_f32 v[58:59], v[50:51], v[62:63]
	v_cvt_pk_bf16_f32 v50, v54, v55
	v_or_b32_e32 v54, v74, v122
	v_ashrrev_i32_e32 v55, 31, v54
	v_lshlrev_b64 v[54:55], 10, v[54:55]
	v_lshl_add_u64 v[54:55], s[76:77], 0, v[54:55]
	v_pk_mul_f32 v[56:57], v[56:57], v[60:61]
	v_pk_mul_f32 v[60:61], v[52:53], v[64:65]
	v_lshl_add_u64 v[54:55], v[54:55], 0, s[20:21]
	v_cvt_pk_bf16_f32 v51, v56, v57
	v_cvt_pk_bf16_f32 v52, v58, v59
	v_cvt_pk_bf16_f32 v53, v60, v61
	v_lshl_add_u64 v[54:55], v[54:55], 0, v[138:139]
	global_store_dwordx4 v[54:55], v[50:53], off sc1
	v_mul_f32_e32 v54, 0x3d372713, v42
	v_mul_f32_e32 v55, 0x3d372713, v43
	v_mul_f32_e32 v50, 0x3d372713, v46
	v_mul_f32_e32 v51, 0x3d372713, v47
	v_mul_f32_e32 v50, v46, v50
	v_mul_f32_e32 v51, v47, v51
	v_mul_f32_e32 v52, 0x3d372713, v48
	v_mul_f32_e32 v53, 0x3d372713, v49
	v_fma_f32 v50, v46, v50, v46
	v_fma_f32 v51, v47, v51, v47
	v_mul_f32_e32 v52, v48, v52
	v_mul_f32_e32 v53, v49, v53
	v_mul_f32_e32 v54, v42, v54
	v_mul_f32_e32 v55, v43, v55
	v_mul_f32_e32 v50, 0x3fcc422a, v50
	v_mul_f32_e32 v51, 0x3fcc422a, v51
	v_fma_f32 v52, v48, v52, v48
	v_fma_f32 v53, v49, v53, v49
	v_fma_f32 v54, v42, v54, v42
	v_fma_f32 v55, v43, v55, v43
	v_mul_f32_e32 v50, 0xbfb8aa3b, v50
	v_mul_f32_e32 v51, 0xbfb8aa3b, v51
	v_mul_f32_e32 v52, 0x3fcc422a, v52
	v_mul_f32_e32 v53, 0x3fcc422a, v53
	v_mul_f32_e32 v54, 0x3fcc422a, v54
	v_mul_f32_e32 v55, 0x3fcc422a, v55
	v_exp_f32_e32 v50, v50
	v_exp_f32_e32 v51, v51
	v_mul_f32_e32 v52, 0xbfb8aa3b, v52
	v_mul_f32_e32 v53, 0xbfb8aa3b, v53
	v_mul_f32_e32 v54, 0xbfb8aa3b, v54
	v_mul_f32_e32 v55, 0xbfb8aa3b, v55
	v_mul_f32_e32 v56, 0x3d372713, v44
	v_mul_f32_e32 v57, 0x3d372713, v45
	v_exp_f32_e32 v52, v52
	v_exp_f32_e32 v53, v53
	v_exp_f32_e32 v54, v54
	v_exp_f32_e32 v55, v55
	v_mul_f32_e32 v56, v44, v56
	v_mul_f32_e32 v57, v45, v57
	v_fma_f32 v56, v44, v56, v44
	v_fma_f32 v57, v45, v57, v45
	v_mul_f32_e32 v56, 0x3fcc422a, v56
	v_mul_f32_e32 v57, 0x3fcc422a, v57
	v_add_f32_e32 v50, 1.0, v50
	v_add_f32_e32 v51, 1.0, v51
	v_mul_f32_e32 v56, 0xbfb8aa3b, v56
	v_mul_f32_e32 v57, 0xbfb8aa3b, v57
	v_rcp_f32_e32 v50, v50
	v_rcp_f32_e32 v51, v51
	v_add_f32_e32 v52, 1.0, v52
	v_add_f32_e32 v53, 1.0, v53
	v_add_f32_e32 v54, 1.0, v54
	v_add_f32_e32 v55, 1.0, v55
	v_exp_f32_e32 v56, v56
	v_exp_f32_e32 v57, v57
	v_rcp_f32_e32 v52, v52
	v_rcp_f32_e32 v53, v53
	v_rcp_f32_e32 v54, v54
	v_rcp_f32_e32 v55, v55
	v_add_u32_e32 v58, 0x1200, v151
	v_add_f32_e32 v56, 1.0, v56
	v_add_f32_e32 v57, 1.0, v57
	v_pk_mul_f32 v[46:47], v[46:47], v[50:51]
	v_rcp_f32_e32 v56, v56
	v_rcp_f32_e32 v57, v57
	v_pk_mul_f32 v[48:49], v[48:49], v[52:53]
	v_pk_mul_f32 v[50:51], v[42:43], v[54:55]
	v_cvt_pk_bf16_f32 v42, v46, v47
	v_or_b32_e32 v46, v58, v150
	v_cvt_pk_bf16_f32 v43, v48, v49
	v_ashrrev_i32_e32 v47, 31, v46
	v_mul_f32_e32 v48, 0x3d372713, v38
	v_mul_f32_e32 v49, 0x3d372713, v39
	v_lshlrev_b64 v[46:47], 10, v[46:47]
	v_mul_f32_e32 v48, v38, v48
	v_mul_f32_e32 v49, v39, v49
	v_lshl_add_u64 v[46:47], s[76:77], 0, v[46:47]
	v_fma_f32 v48, v38, v48, v38
	v_fma_f32 v49, v39, v49, v39
	v_pk_mul_f32 v[52:53], v[44:45], v[56:57]
	v_lshl_add_u64 v[46:47], v[46:47], 0, s[20:21]
	v_mul_f32_e32 v48, 0x3fcc422a, v48
	v_mul_f32_e32 v49, 0x3fcc422a, v49
	v_cvt_pk_bf16_f32 v44, v50, v51
	v_cvt_pk_bf16_f32 v45, v52, v53
	v_lshl_add_u64 v[46:47], v[46:47], 0, v[138:139]
	v_mul_f32_e32 v48, 0xbfb8aa3b, v48
	v_mul_f32_e32 v49, 0xbfb8aa3b, v49
	v_exp_f32_e32 v48, v48
	v_exp_f32_e32 v49, v49
	global_store_dwordx4 v[46:47], v[42:45], off sc1
	v_mul_f32_e32 v46, 0x3d372713, v34
	v_mul_f32_e32 v47, 0x3d372713, v35
	v_mul_f32_e32 v46, v34, v46
	v_mul_f32_e32 v47, v35, v47
	v_fma_f32 v46, v34, v46, v34
	v_fma_f32 v47, v35, v47, v35
	v_mul_f32_e32 v46, 0x3fcc422a, v46
	v_mul_f32_e32 v47, 0x3fcc422a, v47
	v_add_f32_e32 v42, 1.0, v48
	v_add_f32_e32 v43, 1.0, v49
	v_mul_f32_e32 v44, 0x3d372713, v40
	v_mul_f32_e32 v45, 0x3d372713, v41
	v_mul_f32_e32 v46, 0xbfb8aa3b, v46
	v_mul_f32_e32 v47, 0xbfb8aa3b, v47
	v_mul_f32_e32 v48, 0x3d372713, v36
	v_mul_f32_e32 v49, 0x3d372713, v37
	v_mul_f32_e32 v44, v40, v44
	v_mul_f32_e32 v45, v41, v45
	v_exp_f32_e32 v46, v46
	v_exp_f32_e32 v47, v47
	v_mul_f32_e32 v48, v36, v48
	v_mul_f32_e32 v49, v37, v49
	v_fma_f32 v44, v40, v44, v40
	v_fma_f32 v45, v41, v45, v41
	v_fma_f32 v48, v36, v48, v36
	v_fma_f32 v49, v37, v49, v37
	v_mul_f32_e32 v44, 0x3fcc422a, v44
	v_mul_f32_e32 v45, 0x3fcc422a, v45
	v_mul_f32_e32 v48, 0x3fcc422a, v48
	v_mul_f32_e32 v49, 0x3fcc422a, v49
	v_mul_f32_e32 v44, 0xbfb8aa3b, v44
	v_mul_f32_e32 v45, 0xbfb8aa3b, v45
	v_mul_f32_e32 v48, 0xbfb8aa3b, v48
	v_mul_f32_e32 v49, 0xbfb8aa3b, v49
	v_rcp_f32_e32 v42, v42
	v_exp_f32_e32 v44, v44
	v_exp_f32_e32 v45, v45
	v_rcp_f32_e32 v43, v43
	v_add_f32_e32 v46, 1.0, v46
	v_add_f32_e32 v47, 1.0, v47
	v_exp_f32_e32 v48, v48
	v_exp_f32_e32 v49, v49
	v_rcp_f32_e32 v46, v46
	v_rcp_f32_e32 v47, v47
	v_add_f32_e32 v44, 1.0, v44
	v_add_f32_e32 v45, 1.0, v45
	v_add_f32_e32 v48, 1.0, v48
	v_add_f32_e32 v49, 1.0, v49
	v_pk_mul_f32 v[38:39], v[38:39], v[42:43]
	v_rcp_f32_e32 v44, v44
	v_rcp_f32_e32 v45, v45
	v_rcp_f32_e32 v48, v48
	v_rcp_f32_e32 v49, v49
	v_pk_mul_f32 v[42:43], v[34:35], v[46:47]
	v_cvt_pk_bf16_f32 v34, v38, v39
	v_or_b32_e32 v38, v58, v122
	v_ashrrev_i32_e32 v39, 31, v38
	v_lshlrev_b64 v[38:39], 10, v[38:39]
	v_lshl_add_u64 v[38:39], s[76:77], 0, v[38:39]
	v_pk_mul_f32 v[40:41], v[40:41], v[44:45]
	v_pk_mul_f32 v[44:45], v[36:37], v[48:49]
	v_lshl_add_u64 v[38:39], v[38:39], 0, s[20:21]
	v_cvt_pk_bf16_f32 v35, v40, v41
	v_cvt_pk_bf16_f32 v36, v42, v43
	v_cvt_pk_bf16_f32 v37, v44, v45
	v_lshl_add_u64 v[38:39], v[38:39], 0, v[138:139]
	global_store_dwordx4 v[38:39], v[34:37], off sc1
	v_mul_f32_e32 v38, 0x3d372713, v26
	v_mul_f32_e32 v39, 0x3d372713, v27
	v_mul_f32_e32 v34, 0x3d372713, v30
	v_mul_f32_e32 v35, 0x3d372713, v31
	v_mul_f32_e32 v34, v30, v34
	v_mul_f32_e32 v35, v31, v35
	v_mul_f32_e32 v36, 0x3d372713, v32
	v_mul_f32_e32 v37, 0x3d372713, v33
	v_fma_f32 v34, v30, v34, v30
	v_fma_f32 v35, v31, v35, v31
	v_mul_f32_e32 v36, v32, v36
	v_mul_f32_e32 v37, v33, v37
	v_mul_f32_e32 v38, v26, v38
	v_mul_f32_e32 v39, v27, v39
	v_mul_f32_e32 v34, 0x3fcc422a, v34
	v_mul_f32_e32 v35, 0x3fcc422a, v35
	v_fma_f32 v36, v32, v36, v32
	v_fma_f32 v37, v33, v37, v33
	v_fma_f32 v38, v26, v38, v26
	v_fma_f32 v39, v27, v39, v27
	v_mul_f32_e32 v34, 0xbfb8aa3b, v34
	v_mul_f32_e32 v35, 0xbfb8aa3b, v35
	v_mul_f32_e32 v36, 0x3fcc422a, v36
	v_mul_f32_e32 v37, 0x3fcc422a, v37
	v_mul_f32_e32 v38, 0x3fcc422a, v38
	v_mul_f32_e32 v39, 0x3fcc422a, v39
	v_exp_f32_e32 v34, v34
	v_exp_f32_e32 v35, v35
	v_mul_f32_e32 v36, 0xbfb8aa3b, v36
	v_mul_f32_e32 v37, 0xbfb8aa3b, v37
	v_mul_f32_e32 v38, 0xbfb8aa3b, v38
	v_mul_f32_e32 v39, 0xbfb8aa3b, v39
	v_mul_f32_e32 v40, 0x3d372713, v28
	v_mul_f32_e32 v41, 0x3d372713, v29
	v_exp_f32_e32 v36, v36
	v_exp_f32_e32 v37, v37
	v_exp_f32_e32 v38, v38
	v_exp_f32_e32 v39, v39
	v_mul_f32_e32 v40, v28, v40
	v_mul_f32_e32 v41, v29, v41
	v_fma_f32 v40, v28, v40, v28
	v_fma_f32 v41, v29, v41, v29
	v_mul_f32_e32 v40, 0x3fcc422a, v40
	v_mul_f32_e32 v41, 0x3fcc422a, v41
	v_add_f32_e32 v34, 1.0, v34
	v_add_f32_e32 v35, 1.0, v35
	v_mul_f32_e32 v40, 0xbfb8aa3b, v40
	v_mul_f32_e32 v41, 0xbfb8aa3b, v41
	v_rcp_f32_e32 v34, v34
	v_rcp_f32_e32 v35, v35
	v_add_f32_e32 v36, 1.0, v36
	v_add_f32_e32 v37, 1.0, v37
	v_add_f32_e32 v38, 1.0, v38
	v_add_f32_e32 v39, 1.0, v39
	v_exp_f32_e32 v40, v40
	v_exp_f32_e32 v41, v41
	v_rcp_f32_e32 v36, v36
	v_rcp_f32_e32 v37, v37
	v_rcp_f32_e32 v38, v38
	v_rcp_f32_e32 v39, v39
	v_add_u32_e32 v42, 0x1400, v151
	v_add_f32_e32 v40, 1.0, v40
	v_add_f32_e32 v41, 1.0, v41
	v_pk_mul_f32 v[30:31], v[30:31], v[34:35]
	v_rcp_f32_e32 v40, v40
	v_rcp_f32_e32 v41, v41
	v_pk_mul_f32 v[32:33], v[32:33], v[36:37]
	v_pk_mul_f32 v[34:35], v[26:27], v[38:39]
	v_cvt_pk_bf16_f32 v26, v30, v31
	v_or_b32_e32 v30, v42, v150
	v_cvt_pk_bf16_f32 v27, v32, v33
	v_ashrrev_i32_e32 v31, 31, v30
	v_mul_f32_e32 v32, 0x3d372713, v22
	v_mul_f32_e32 v33, 0x3d372713, v23
	v_lshlrev_b64 v[30:31], 10, v[30:31]
	v_mul_f32_e32 v32, v22, v32
	v_mul_f32_e32 v33, v23, v33
	v_lshl_add_u64 v[30:31], s[76:77], 0, v[30:31]
	v_fma_f32 v32, v22, v32, v22
	v_fma_f32 v33, v23, v33, v23
	v_pk_mul_f32 v[36:37], v[28:29], v[40:41]
	v_lshl_add_u64 v[30:31], v[30:31], 0, s[20:21]
	v_mul_f32_e32 v32, 0x3fcc422a, v32
	v_mul_f32_e32 v33, 0x3fcc422a, v33
	v_cvt_pk_bf16_f32 v28, v34, v35
	v_cvt_pk_bf16_f32 v29, v36, v37
	v_lshl_add_u64 v[30:31], v[30:31], 0, v[138:139]
	v_mul_f32_e32 v32, 0xbfb8aa3b, v32
	v_mul_f32_e32 v33, 0xbfb8aa3b, v33
	v_exp_f32_e32 v32, v32
	v_exp_f32_e32 v33, v33
	global_store_dwordx4 v[30:31], v[26:29], off sc1
	v_mul_f32_e32 v30, 0x3d372713, v18
	v_mul_f32_e32 v31, 0x3d372713, v19
	v_mul_f32_e32 v30, v18, v30
	v_mul_f32_e32 v31, v19, v31
	v_fma_f32 v30, v18, v30, v18
	v_fma_f32 v31, v19, v31, v19
	v_mul_f32_e32 v30, 0x3fcc422a, v30
	v_mul_f32_e32 v31, 0x3fcc422a, v31
	v_add_f32_e32 v26, 1.0, v32
	v_add_f32_e32 v27, 1.0, v33
	v_mul_f32_e32 v28, 0x3d372713, v24
	v_mul_f32_e32 v29, 0x3d372713, v25
	v_mul_f32_e32 v30, 0xbfb8aa3b, v30
	v_mul_f32_e32 v31, 0xbfb8aa3b, v31
	v_mul_f32_e32 v32, 0x3d372713, v20
	v_mul_f32_e32 v33, 0x3d372713, v21
	v_mul_f32_e32 v28, v24, v28
	v_mul_f32_e32 v29, v25, v29
	v_exp_f32_e32 v30, v30
	v_exp_f32_e32 v31, v31
	v_mul_f32_e32 v32, v20, v32
	v_mul_f32_e32 v33, v21, v33
	v_fma_f32 v28, v24, v28, v24
	v_fma_f32 v29, v25, v29, v25
	v_fma_f32 v32, v20, v32, v20
	v_fma_f32 v33, v21, v33, v21
	v_mul_f32_e32 v28, 0x3fcc422a, v28
	v_mul_f32_e32 v29, 0x3fcc422a, v29
	v_mul_f32_e32 v32, 0x3fcc422a, v32
	v_mul_f32_e32 v33, 0x3fcc422a, v33
	v_mul_f32_e32 v28, 0xbfb8aa3b, v28
	v_mul_f32_e32 v29, 0xbfb8aa3b, v29
	v_mul_f32_e32 v32, 0xbfb8aa3b, v32
	v_mul_f32_e32 v33, 0xbfb8aa3b, v33
	v_rcp_f32_e32 v26, v26
	v_exp_f32_e32 v28, v28
	v_exp_f32_e32 v29, v29
	v_rcp_f32_e32 v27, v27
	v_add_f32_e32 v30, 1.0, v30
	v_add_f32_e32 v31, 1.0, v31
	v_exp_f32_e32 v32, v32
	v_exp_f32_e32 v33, v33
	v_rcp_f32_e32 v30, v30
	v_rcp_f32_e32 v31, v31
	v_add_f32_e32 v28, 1.0, v28
	v_add_f32_e32 v29, 1.0, v29
	v_add_f32_e32 v32, 1.0, v32
	v_add_f32_e32 v33, 1.0, v33
	v_pk_mul_f32 v[22:23], v[22:23], v[26:27]
	v_rcp_f32_e32 v28, v28
	v_rcp_f32_e32 v29, v29
	v_rcp_f32_e32 v32, v32
	v_rcp_f32_e32 v33, v33
	v_pk_mul_f32 v[26:27], v[18:19], v[30:31]
	v_cvt_pk_bf16_f32 v18, v22, v23
	v_or_b32_e32 v22, v42, v122
	v_ashrrev_i32_e32 v23, 31, v22
	v_lshlrev_b64 v[22:23], 10, v[22:23]
	v_lshl_add_u64 v[22:23], s[76:77], 0, v[22:23]
	v_pk_mul_f32 v[24:25], v[24:25], v[28:29]
	v_pk_mul_f32 v[28:29], v[20:21], v[32:33]
	v_lshl_add_u64 v[22:23], v[22:23], 0, s[20:21]
	v_cvt_pk_bf16_f32 v19, v24, v25
	v_cvt_pk_bf16_f32 v20, v26, v27
	v_cvt_pk_bf16_f32 v21, v28, v29
	v_lshl_add_u64 v[22:23], v[22:23], 0, v[138:139]
	global_store_dwordx4 v[22:23], v[18:21], off sc1
	v_mul_f32_e32 v22, 0x3d372713, v10
	v_mul_f32_e32 v23, 0x3d372713, v11
	v_mul_f32_e32 v18, 0x3d372713, v14
	v_mul_f32_e32 v19, 0x3d372713, v15
	v_mul_f32_e32 v18, v14, v18
	v_mul_f32_e32 v19, v15, v19
	v_mul_f32_e32 v20, 0x3d372713, v16
	v_mul_f32_e32 v21, 0x3d372713, v17
	v_fma_f32 v18, v14, v18, v14
	v_fma_f32 v19, v15, v19, v15
	v_mul_f32_e32 v20, v16, v20
	v_mul_f32_e32 v21, v17, v21
	v_mul_f32_e32 v22, v10, v22
	v_mul_f32_e32 v23, v11, v23
	v_mul_f32_e32 v18, 0x3fcc422a, v18
	v_mul_f32_e32 v19, 0x3fcc422a, v19
	v_fma_f32 v20, v16, v20, v16
	v_fma_f32 v21, v17, v21, v17
	v_fma_f32 v22, v10, v22, v10
	v_fma_f32 v23, v11, v23, v11
	v_mul_f32_e32 v18, 0xbfb8aa3b, v18
	v_mul_f32_e32 v19, 0xbfb8aa3b, v19
	v_mul_f32_e32 v20, 0x3fcc422a, v20
	v_mul_f32_e32 v21, 0x3fcc422a, v21
	v_mul_f32_e32 v22, 0x3fcc422a, v22
	v_mul_f32_e32 v23, 0x3fcc422a, v23
	v_exp_f32_e32 v18, v18
	v_exp_f32_e32 v19, v19
	v_mul_f32_e32 v20, 0xbfb8aa3b, v20
	v_mul_f32_e32 v21, 0xbfb8aa3b, v21
	v_mul_f32_e32 v22, 0xbfb8aa3b, v22
	v_mul_f32_e32 v23, 0xbfb8aa3b, v23
	v_mul_f32_e32 v24, 0x3d372713, v12
	v_mul_f32_e32 v25, 0x3d372713, v13
	v_exp_f32_e32 v20, v20
	v_exp_f32_e32 v21, v21
	v_exp_f32_e32 v22, v22
	v_exp_f32_e32 v23, v23
	v_mul_f32_e32 v24, v12, v24
	v_mul_f32_e32 v25, v13, v25
	v_fma_f32 v24, v12, v24, v12
	v_fma_f32 v25, v13, v25, v13
	v_mul_f32_e32 v24, 0x3fcc422a, v24
	v_mul_f32_e32 v25, 0x3fcc422a, v25
	v_add_f32_e32 v18, 1.0, v18
	v_add_f32_e32 v19, 1.0, v19
	v_mul_f32_e32 v24, 0xbfb8aa3b, v24
	v_mul_f32_e32 v25, 0xbfb8aa3b, v25
	v_rcp_f32_e32 v18, v18
	v_rcp_f32_e32 v19, v19
	v_add_f32_e32 v20, 1.0, v20
	v_add_f32_e32 v21, 1.0, v21
	v_add_f32_e32 v22, 1.0, v22
	v_add_f32_e32 v23, 1.0, v23
	v_exp_f32_e32 v24, v24
	v_exp_f32_e32 v25, v25
	v_rcp_f32_e32 v20, v20
	v_rcp_f32_e32 v21, v21
	v_rcp_f32_e32 v22, v22
	v_rcp_f32_e32 v23, v23
	v_add_u32_e32 v26, 0x1600, v151
	v_add_f32_e32 v24, 1.0, v24
	v_add_f32_e32 v25, 1.0, v25
	v_pk_mul_f32 v[14:15], v[14:15], v[18:19]
	v_rcp_f32_e32 v24, v24
	v_rcp_f32_e32 v25, v25
	v_pk_mul_f32 v[16:17], v[16:17], v[20:21]
	v_pk_mul_f32 v[18:19], v[10:11], v[22:23]
	v_cvt_pk_bf16_f32 v10, v14, v15
	v_or_b32_e32 v14, v26, v150
	v_cvt_pk_bf16_f32 v11, v16, v17
	v_ashrrev_i32_e32 v15, 31, v14
	v_mul_f32_e32 v16, 0x3d372713, v6
	v_mul_f32_e32 v17, 0x3d372713, v7
	v_lshlrev_b64 v[14:15], 10, v[14:15]
	v_mul_f32_e32 v16, v6, v16
	v_mul_f32_e32 v17, v7, v17
	v_lshl_add_u64 v[14:15], s[76:77], 0, v[14:15]
	v_fma_f32 v16, v6, v16, v6
	v_fma_f32 v17, v7, v17, v7
	v_pk_mul_f32 v[20:21], v[12:13], v[24:25]
	v_lshl_add_u64 v[14:15], v[14:15], 0, s[20:21]
	v_mul_f32_e32 v16, 0x3fcc422a, v16
	v_mul_f32_e32 v17, 0x3fcc422a, v17
	v_cvt_pk_bf16_f32 v12, v18, v19
	v_cvt_pk_bf16_f32 v13, v20, v21
	v_lshl_add_u64 v[14:15], v[14:15], 0, v[138:139]
	v_mul_f32_e32 v16, 0xbfb8aa3b, v16
	v_mul_f32_e32 v17, 0xbfb8aa3b, v17
	v_exp_f32_e32 v16, v16
	v_exp_f32_e32 v17, v17
	global_store_dwordx4 v[14:15], v[10:13], off sc1
	v_mul_f32_e32 v14, 0x3d372713, v2
	v_mul_f32_e32 v15, 0x3d372713, v3
	v_mul_f32_e32 v14, v2, v14
	v_mul_f32_e32 v15, v3, v15
	v_fma_f32 v14, v2, v14, v2
	v_fma_f32 v15, v3, v15, v3
	v_mul_f32_e32 v14, 0x3fcc422a, v14
	v_mul_f32_e32 v15, 0x3fcc422a, v15
	v_add_f32_e32 v10, 1.0, v16
	v_add_f32_e32 v11, 1.0, v17
	v_mul_f32_e32 v12, 0x3d372713, v8
	v_mul_f32_e32 v13, 0x3d372713, v9
	v_mul_f32_e32 v14, 0xbfb8aa3b, v14
	v_mul_f32_e32 v15, 0xbfb8aa3b, v15
	v_mul_f32_e32 v16, 0x3d372713, v4
	v_mul_f32_e32 v17, 0x3d372713, v5
	v_mul_f32_e32 v12, v8, v12
	v_mul_f32_e32 v13, v9, v13
	v_exp_f32_e32 v14, v14
	v_exp_f32_e32 v15, v15
	v_mul_f32_e32 v16, v4, v16
	v_mul_f32_e32 v17, v5, v17
	v_fma_f32 v12, v8, v12, v8
	v_fma_f32 v13, v9, v13, v9
	v_fma_f32 v16, v4, v16, v4
	v_fma_f32 v17, v5, v17, v5
	v_mul_f32_e32 v12, 0x3fcc422a, v12
	v_mul_f32_e32 v13, 0x3fcc422a, v13
	v_mul_f32_e32 v16, 0x3fcc422a, v16
	v_mul_f32_e32 v17, 0x3fcc422a, v17
	v_mul_f32_e32 v12, 0xbfb8aa3b, v12
	v_mul_f32_e32 v13, 0xbfb8aa3b, v13
	v_mul_f32_e32 v16, 0xbfb8aa3b, v16
	v_mul_f32_e32 v17, 0xbfb8aa3b, v17
	v_rcp_f32_e32 v10, v10
	v_exp_f32_e32 v12, v12
	v_exp_f32_e32 v13, v13
	v_rcp_f32_e32 v11, v11
	v_add_f32_e32 v14, 1.0, v14
	v_add_f32_e32 v15, 1.0, v15
	v_exp_f32_e32 v16, v16
	v_exp_f32_e32 v17, v17
	v_rcp_f32_e32 v14, v14
	v_rcp_f32_e32 v15, v15
	v_add_f32_e32 v12, 1.0, v12
	v_add_f32_e32 v13, 1.0, v13
	v_add_f32_e32 v16, 1.0, v16
	v_add_f32_e32 v17, 1.0, v17
	v_pk_mul_f32 v[6:7], v[6:7], v[10:11]
	v_rcp_f32_e32 v12, v12
	v_rcp_f32_e32 v13, v13
	v_rcp_f32_e32 v16, v16
	v_rcp_f32_e32 v17, v17
	v_pk_mul_f32 v[10:11], v[2:3], v[14:15]
	v_cvt_pk_bf16_f32 v2, v6, v7
	v_or_b32_e32 v6, v26, v122
	v_ashrrev_i32_e32 v7, 31, v6
	v_lshlrev_b64 v[6:7], 10, v[6:7]
	v_lshl_add_u64 v[6:7], s[76:77], 0, v[6:7]
	v_pk_mul_f32 v[8:9], v[8:9], v[12:13]
	v_pk_mul_f32 v[12:13], v[4:5], v[16:17]
	v_lshl_add_u64 v[6:7], v[6:7], 0, s[20:21]
	v_cvt_pk_bf16_f32 v3, v8, v9
	v_cvt_pk_bf16_f32 v4, v10, v11
	v_cvt_pk_bf16_f32 v5, v12, v13
	v_lshl_add_u64 v[6:7], v[6:7], 0, v[138:139]
	global_store_dwordx4 v[6:7], v[2:5], off sc1
	s_cbranch_vccnz .LBB0_421
	s_andn2_b64 vcc, exec, s[6:7]
	s_cbranch_vccnz .LBB0_420
	s_barrier
	s_branch .LBB0_420
